# GEMM prologues de-serialised (K-tile 1 DMAs issued before the first wait, wait vmcnt(2)->vmcnt(8), compiler vmcnt(0) drain removed) + SwiGLU epilogue address trim
# speedup vs baseline: 1.0016x; 1.0016x over previous
.LBB0_141:
	s_add_u32 s14, s10, 0x4c800000
	s_addc_u32 s15, s11, 0
	s_add_u32 s16, s10, 0x62980000
	s_addc_u32 s17, s11, 0
	s_and_b32 s5, s1, 3
	s_lshl_b32 s57, s2, 6
	s_lshl_b32 s24, s2, 13
	s_lshl_b32 s25, s5, 12
	s_cmp_lt_u32 s1, 4
	s_cselect_b64 s[18:19], -1, 0
	s_lshl_b32 s2, s2, 11
	s_add_i32 s2, s2, 0
	s_lshl_b32 s20, s5, 9
	s_add_i32 s58, s2, s20
	s_add_i32 s58, s58, 0x20400
	s_cmp_eq_u32 s5, 0
	s_cselect_b64 s[20:21], -1, 0
	s_lshl_b32 s22, s5, 2
	s_add_i32 s2, s2, s22
	v_lshl_add_u64 v[10:11], v[10:11], 0, s[66:67]
	s_add_i32 m0, s53, 0x18000
	s_add_i32 s2, s2, 0x21400
	s_lshl_b32 s60, s5, 7
	s_ashr_i32 s64, s0, 31
	global_load_lds_dwordx4 v[10:11], off
	v_lshl_add_u64 v[8:9], v[8:9], 0, s[66:67]
	s_add_i32 m0, s53, 0x1a000
	s_add_i32 s65, s53, 0x8000
	s_add_i32 s68, s53, 0xa000
	global_load_lds_dwordx4 v[8:9], off
	v_lshl_add_u64 v[6:7], v[6:7], 0, s[66:67]
	s_mov_b32 m0, s65
	s_add_u32 s22, s42, 0x80080
	global_load_lds_dwordx4 v[6:7], off
	v_lshl_add_u64 v[4:5], v[4:5], 0, s[66:67]
	s_mov_b32 m0, s68
	s_addc_u32 s23, s43, 0
	global_load_lds_dwordx4 v[4:5], off
	v_lshl_add_u64 v[4:5], s[22:23], 0, v[2:3]
	s_add_i32 m0, s53, 0x1c000
	v_and_b32_e32 v6, 15, v12
	global_load_lds_dwordx4 v[4:5], off
	v_lshl_add_u64 v[4:5], s[22:23], 0, v[142:143]
	s_add_i32 m0, s53, 0x1e000
	v_bfe_u32 v7, v12, 4, 2
	global_load_lds_dwordx4 v[4:5], off
	s_waitcnt vmcnt(8)
	s_barrier
	v_lshlrev_b32_e32 v4, 4, v7
	v_lshlrev_b32_e32 v5, 2, v6
	v_lshl_or_b32 v4, v6, 6, v4
	v_and_b32_e32 v9, 32, v5
	v_lshlrev_b32_e32 v144, 5, v7
	v_mov_b32_e32 v145, v3
	v_bitop3_b32 v10, v4, s24, v9 bitop3:0xde
	v_bitop3_b32 v169, v4, s25, v9 bitop3:0xde
	v_add_u32_e32 v170, s58, v5
	v_lshl_add_u64 v[4:5], s[10:11], 0, v[144:145]
	s_mov_b64 s[22:23], 0x300000
	v_or_b32_e32 v168, s57, v6
	v_lshl_add_u64 v[146:147], v[4:5], 0, s[22:23]
	v_lshlrev_b32_e32 v4, 5, v6
	v_lshlrev_b32_e32 v6, 15, v13
	v_and_b32_e32 v6, 0xffff0000, v6
	v_lshlrev_b32_e32 v8, 3, v7
	v_cmp_gt_u32_e32 vcc, 2, v7
	v_cmp_eq_u32_e64 s[34:35], 0, v7
	v_lshl_add_u32 v6, v14, 12, v6
	v_and_b32_e32 v7, 1, v13
	v_lshl_or_b32 v6, v7, 6, v6
	v_lshl_add_u32 v148, v15, 1, v6
	v_lshlrev_b32_e32 v6, 15, v16
	v_and_b32_e32 v6, 0xffff0000, v6
	s_waitcnt vmcnt(6)
	v_lshlrev_b32_e32 v5, 5, v168
	v_lshl_add_u32 v6, v17, 12, v6
	v_and_b32_e32 v7, 1, v16
	v_lshl_or_b32 v6, v7, 6, v6
	v_add_u32_e32 v5, 0, v5
	s_mov_b32 s69, 0
	s_and_b64 s[20:21], s[20:21], vcc
	v_lshl_or_b32 v145, s5, 5, v8
	v_mov_b32_e32 v149, v3
	v_lshl_add_u32 v150, v18, 1, v6
	v_mov_b32_e32 v151, v3
	s_mov_b32 s70, -1
	v_add_u32_e32 v171, 0, v10
	v_add_u32_e32 v172, 0x21400, v5
	v_add_u32_e32 v173, s2, v4
	s_barrier
	s_branch .LBB0_144

.LBB0_205:
	s_lshl_b32 s14, s46, 17
	v_readlane_b32 s20, v254, 46
	s_add_i32 s58, s14, s20
	v_readlane_b32 s21, v254, 47
	s_add_u32 s14, s10, 0x35800000
	s_addc_u32 s15, s11, 0
	s_lshl_b64 s[20:21], s[58:59], 2
	s_add_u32 s10, s10, s20
	s_addc_u32 s11, s11, s21
	s_add_u32 s10, s10, 0x62800000
	s_addc_u32 s11, s11, 0
	s_and_b32 s19, s1, 3
	s_add_i32 m0, s43, 0x18000
	v_lshl_add_u64 v[10:11], v[10:11], 0, s[66:67]
	s_lshl_b32 s46, s18, 6
	s_lshl_b32 s17, s18, 13
	s_lshl_b32 s22, s19, 12
	global_load_lds_dwordx4 v[10:11], off
	v_lshl_add_u64 v[8:9], v[8:9], 0, s[66:67]
	s_add_i32 m0, s43, 0x1a000
	s_add_i32 s48, s43, 0x8000
	s_add_i32 s49, s43, 0xa000
	global_load_lds_dwordx4 v[8:9], off
	v_lshl_add_u64 v[4:5], v[4:5], 0, s[66:67]
	s_mov_b32 m0, s48
	s_add_u32 s20, s30, 0x80080
	global_load_lds_dwordx4 v[4:5], off
	v_lshl_add_u64 v[4:5], v[6:7], 0, s[66:67]
	s_mov_b32 m0, s49
	s_addc_u32 s21, s31, 0
	global_load_lds_dwordx4 v[4:5], off
	s_add_i32 m0, s43, 0x1c000
	v_lshl_add_u64 v[4:5], s[20:21], 0, v[2:3]
	global_load_lds_dwordx4 v[4:5], off
	v_lshl_add_u64 v[4:5], s[20:21], 0, v[0:1]
	s_add_i32 m0, s43, 0x1e000
	s_cmp_lt_u32 s1, 4
	global_load_lds_dwordx4 v[4:5], off
	s_waitcnt vmcnt(8)
	s_barrier
	v_lshrrev_b32_e32 v5, 1, v14
	v_and_b32_e32 v5, 24, v5
	v_and_b32_e32 v4, 15, v14
	v_lshlrev_b32_e32 v6, 1, v5
	v_or_b32_e32 v150, s46, v4
	v_lshl_or_b32 v6, v4, 6, v6
	v_lshlrev_b32_e32 v4, 2, v4
	v_and_b32_e32 v7, 32, v4
	s_sext_i32_i16 s27, s16
	v_bitop3_b32 v8, v6, s17, v7 bitop3:0xde
	s_cselect_b64 s[16:17], -1, 0
	s_lshl_b32 s1, s18, 11
	s_add_i32 s1, s1, 0
	s_lshl_b32 s18, s19, 9
	s_add_i32 s1, s1, s18
	s_add_i32 s1, s1, 0x20400
	s_waitcnt lgkmcnt(0)
	v_add_u32_e32 v152, s1, v4
	v_lshlrev_b32_e32 v4, 15, v16
	v_and_b32_e32 v4, 0xffff0000, v4
	v_lshl_or_b32 v153, s19, 5, v5
	v_lshl_add_u32 v4, v17, 12, v4
	v_and_b32_e32 v5, 1, v16
	v_lshl_or_b32 v4, v5, 6, v4
	v_lshl_add_u32 v136, v18, 1, v4
	v_lshlrev_b32_e32 v4, 15, v12
	v_and_b32_e32 v4, 0xffff0000, v4
	s_waitcnt vmcnt(6)
	v_lshl_add_u32 v4, v13, 12, v4
	v_and_b32_e32 v5, 1, v12
	v_lshl_or_b32 v4, v5, 6, v4
	v_bitop3_b32 v151, v6, s22, v7 bitop3:0xde
	v_mov_b32_e32 v137, v3
	v_lshl_add_u32 v138, v15, 1, v4
	v_mov_b32_e32 v139, v3
	s_mov_b32 s50, 0
	s_mov_b32 s51, -1
	v_add_u32_e32 v154, 0, v8
	s_barrier
	s_branch .LBB0_208

.LBB0_287:
	v_readlane_b32 s6, v253, 26
	v_readlane_b32 s7, v253, 27
	s_and_b64 s[6:7], s[6:7], exec
	v_readlane_b32 s7, v253, 24
	s_cselect_b32 s6, 1, 3
	s_mul_i32 s7, s7, 3
	s_lshl_b32 s12, s27, 5
	s_add_i32 s58, s7, s6
	s_and_b32 s14, s12, 0x60
	s_add_i32 m0, s28, 0x18000
	v_lshl_add_u64 v[10:11], v[10:11], 0, s[66:67]
	s_lshl_b64 s[6:7], s[58:59], 18
	s_lshl_b32 s11, s10, 13
	s_lshl_b32 s15, s14, 7
	global_load_lds_dwordx4 v[10:11], off
	v_lshl_add_u64 v[8:9], v[8:9], 0, s[66:67]
	s_add_i32 m0, s28, 0x1a000
	s_add_i32 s34, s28, 0x8000
	s_add_i32 s35, s28, 0xa000
	global_load_lds_dwordx4 v[8:9], off
	v_lshl_add_u64 v[4:5], v[4:5], 0, s[66:67]
	s_mov_b32 m0, s34
	s_add_u32 s12, s18, 0x160080
	global_load_lds_dwordx4 v[4:5], off
	v_lshl_add_u64 v[4:5], v[6:7], 0, s[66:67]
	s_mov_b32 m0, s35
	s_addc_u32 s13, s19, 0
	global_load_lds_dwordx4 v[4:5], off
	s_add_i32 m0, s28, 0x1c000
	v_lshl_add_u64 v[4:5], s[12:13], 0, v[2:3]
	global_load_lds_dwordx4 v[4:5], off
	v_lshl_add_u64 v[4:5], s[12:13], 0, v[190:191]
	s_add_i32 m0, s28, 0x1e000
	s_mov_b64 s[20:21], 0x160080
	global_load_lds_dwordx4 v[4:5], off
	s_waitcnt vmcnt(8)
	s_barrier
	v_bfe_u32 v4, v12, 4, 2
	v_and_b32_e32 v5, 15, v12
	v_lshlrev_b32_e32 v6, 4, v4
	v_lshl_or_b32 v218, s10, 6, v5
	v_lshl_or_b32 v5, v5, 6, v6
	v_lshlrev_b32_e32 v6, 2, v12
	v_and_b32_e32 v6, 32, v6
	v_bitop3_b32 v219, v5, s15, v6 bitop3:0xde
	s_movk_i32 s15, 0x1600
	v_bitop3_b32 v7, v5, s11, v6 bitop3:0xde
	v_cmp_eq_u32_e64 s[36:37], 0, v4
	v_lshl_or_b32 v220, v4, 3, s14
	v_lshrrev_b32_e32 v5, 1, v13
	v_mul_lo_u32 v4, v15, s15
	s_mov_b32 s14, 0x16000
	v_mad_u64_u32 v[4:5], s[12:13], v5, s14, v[4:5]
	v_or_b32_e32 v4, v4, v14
	v_add_lshl_u32 v4, v4, v16, 1
	v_mov_b32_e32 v5, v3
	v_lshl_add_u64 v[192:193], v[4:5], 0, s[20:21]
	v_lshrrev_b32_e32 v5, 1, v17
	v_mul_lo_u32 v4, v19, s15
	v_mad_u64_u32 v[4:5], s[12:13], v5, s14, v[4:5]
	s_waitcnt vmcnt(6)
	v_or_b32_e32 v4, v4, v18
	s_cmp_lt_u32 s27, 4
	v_add_lshl_u32 v4, v4, v20, 1
	v_mov_b32_e32 v5, v3
	s_cselect_b64 s[10:11], -1, 0
	s_mov_b32 s42, 0
	s_ashr_i32 s43, s0, 31
	v_lshl_add_u64 v[194:195], v[4:5], 0, s[20:21]
	v_add_u32_e32 v221, 0, v7
	s_barrier
	s_branch .LBB0_290

.LBB0_333:
	v_lshrrev_b32_e32 v22, 1, v20
	v_and_b32_e32 v22, 24, v22
	v_and_b32_e32 v21, 15, v20
	v_lshlrev_b32_e32 v23, 1, v22
	v_lshlrev_b32_e32 v20, 2, v20
	v_lshl_or_b32 v235, s6, 6, v21
	v_lshl_or_b32 v21, v21, 6, v23
	s_lshl_b32 s6, s6, 13
	v_and_b32_e32 v20, 32, v20
	v_bitop3_b32 v23, v21, s6, v20 bitop3:0xde
	s_lshl_b32 s6, s27, 5
	s_and_b32 s10, s6, 0x60
	s_add_i32 m0, s23, 0x18000
	v_lshl_add_u64 v[10:11], v[10:11], 0, s[66:67]
	s_lshl_b32 s6, s10, 7
	global_load_lds_dwordx4 v[10:11], off
	v_lshl_add_u64 v[8:9], v[8:9], 0, s[66:67]
	s_add_i32 m0, s23, 0x1a000
	s_add_i32 s31, s23, 0x8000
	s_add_i32 s34, s23, 0xa000
	v_bitop3_b32 v236, v21, s6, v20 bitop3:0xde
	global_load_lds_dwordx4 v[8:9], off
	v_lshl_add_u64 v[4:5], v[4:5], 0, s[66:67]
	s_mov_b32 m0, s31
	s_add_u32 s6, s16, 0x160080
	s_sext_i32_i8 s42, s7
	global_load_lds_dwordx4 v[4:5], off
	v_lshl_add_u64 v[4:5], v[6:7], 0, s[66:67]
	s_mov_b32 m0, s34
	s_addc_u32 s7, s17, 0
	global_load_lds_dwordx4 v[4:5], off
	s_add_i32 m0, s23, 0x1c000
	v_lshl_add_u64 v[4:5], s[6:7], 0, v[2:3]
	global_load_lds_dwordx4 v[4:5], off
	v_lshl_add_u64 v[4:5], s[6:7], 0, v[198:199]
	s_add_i32 m0, s23, 0x1e000
	s_movk_i32 s13, 0x1600
	global_load_lds_dwordx4 v[4:5], off
	s_waitcnt vmcnt(8)
	s_barrier
	v_lshrrev_b32_e32 v5, 1, v12
	v_mul_lo_u32 v4, v14, s13
	s_mov_b32 s12, 0x16000
	v_or_b32_e32 v237, s10, v22
	v_mad_u64_u32 v[4:5], s[10:11], v5, s12, v[4:5]
	v_or_b32_e32 v4, v4, v13
	v_add_lshl_u32 v4, v4, v15, 1
	v_mov_b32_e32 v5, v3
	s_mov_b64 s[18:19], 0x160080
	v_lshl_add_u64 v[200:201], v[4:5], 0, s[18:19]
	v_lshrrev_b32_e32 v5, 1, v16
	v_mul_lo_u32 v4, v18, s13
	v_mad_u64_u32 v[4:5], s[10:11], v5, s12, v[4:5]
	s_waitcnt vmcnt(6)
	v_or_b32_e32 v4, v4, v17
	s_cmp_lt_u32 s27, 4
	v_add_lshl_u32 v4, v4, v19, 1
	v_mov_b32_e32 v5, v3
	s_cselect_b64 s[6:7], -1, 0
	v_lshl_add_u64 v[202:203], v[4:5], 0, s[18:19]
	s_mov_b32 s27, 0
	v_add_u32_e32 v238, 0, v23
	s_barrier
	s_branch .LBB0_336

.LBB0_424:
	v_readlane_b32 s18, v254, 46
	s_add_u32 s16, s34, 0x35800000
	v_readlane_b32 s19, v254, 47
	s_addc_u32 s17, s35, 0
	s_lshl_b64 s[18:19], s[18:19], 2
	s_add_u32 s5, s34, s18
	s_addc_u32 s19, s35, s19
	s_add_u32 s18, s5, 0x62840000
	s_addc_u32 s19, s19, 0
	s_and_b32 s5, s1, 3
	s_lshl_b32 s2, s2, 11
	s_add_i32 s2, s2, 0
	s_lshl_b32 s20, s5, 9
	s_add_i32 s56, s2, s20
	s_lshl_b32 s20, s5, 2
	s_add_i32 s2, s2, s20
	v_lshl_add_u64 v[10:11], v[10:11], 0, s[66:67]
	s_add_i32 m0, s15, 0x18000
	s_lshl_b32 s22, s5, 5
	s_lshl_b32 s23, s5, 12
	s_add_i32 s56, s56, 0x20400
	s_add_i32 s24, s2, 0x21400
	s_lshl_b32 s57, s5, 7
	s_ashr_i32 s58, s44, 31
	global_load_lds_dwordx4 v[10:11], off
	v_lshl_add_u64 v[8:9], v[8:9], 0, s[66:67]
	s_add_i32 m0, s15, 0x1a000
	s_add_i32 s60, s15, 0x8000
	s_add_i32 s64, s15, 0xa000
	global_load_lds_dwordx4 v[8:9], off
	v_lshl_add_u64 v[4:5], v[4:5], 0, s[66:67]
	s_mov_b32 m0, s60
	s_add_u32 s20, s30, 0x80080
	global_load_lds_dwordx4 v[4:5], off
	v_lshl_add_u64 v[4:5], v[6:7], 0, s[66:67]
	s_mov_b32 m0, s64
	s_addc_u32 s21, s31, 0
	global_load_lds_dwordx4 v[4:5], off
	v_lshl_add_u64 v[4:5], s[20:21], 0, v[2:3]
	s_add_i32 m0, s15, 0x1c000
	s_movk_i32 s2, 0x3c0
	global_load_lds_dwordx4 v[4:5], off
	v_lshl_add_u64 v[4:5], s[20:21], 0, v[142:143]
	s_add_i32 m0, s15, 0x1e000
	s_mov_b32 s65, 0
	global_load_lds_dwordx4 v[4:5], off
	s_waitcnt vmcnt(8)
	s_barrier
	v_and_b32_e32 v4, 15, v12
	v_bfe_u32 v5, v12, 4, 2
	v_or_b32_e32 v162, s46, v4
	v_lshlrev_b32_e32 v6, 6, v162
	v_lshlrev_b32_e32 v7, 4, v5
	v_lshlrev_b32_e32 v8, 2, v162
	v_and_or_b32 v6, v6, s2, v7
	v_and_b32_e32 v8, 32, v8
	v_bitop3_b32 v6, v6, s45, v8 bitop3:0xde
	v_lshlrev_b32_e32 v8, 2, v4
	v_lshl_or_b32 v7, v4, 6, v7
	v_and_b32_e32 v9, 32, v8
	v_bitop3_b32 v163, v7, s23, v9 bitop3:0xde
	v_lshlrev_b32_e32 v7, 15, v13
	v_and_b32_e32 v7, 0xffff0000, v7
	v_add_u32_e32 v165, s56, v8
	v_lshl_add_u32 v7, v14, 12, v7
	v_and_b32_e32 v8, 1, v13
	v_lshl_or_b32 v7, v8, 6, v7
	v_lshl_add_u32 v144, v15, 1, v7
	v_lshlrev_b32_e32 v7, 15, v16
	v_and_b32_e32 v7, 0xffff0000, v7
	s_waitcnt vmcnt(6)
	v_lshl_or_b32 v164, v5, 3, s22
	v_cmp_eq_u32_e64 s[38:39], 0, v5
	v_lshlrev_b32_e32 v166, 5, v5
	v_lshlrev_b32_e32 v5, 5, v162
	v_lshl_add_u32 v7, v17, 12, v7
	v_and_b32_e32 v8, 1, v16
	v_lshlrev_b32_e32 v4, 5, v4
	v_lshl_or_b32 v7, v8, 6, v7
	v_add_u32_e32 v5, 0, v5
	v_mov_b32_e32 v145, v3
	v_lshl_add_u32 v146, v18, 1, v7
	v_mov_b32_e32 v147, v3
	s_mov_b32 s2, -1
	v_add_u32_e32 v167, 0, v6
	v_add_u32_e32 v168, 0x21400, v5
	v_add_u32_e32 v169, s24, v4
	s_barrier
	s_branch .LBB0_427

.LBB0_485:
	s_sext_i32_i8 s13, s4
	s_add_u32 s4, s34, 0x1000000
	s_addc_u32 s5, s35, 0
	v_bfe_u32 v20, v18, 4, 2
	s_lshl_b32 s1, s1, 5
	v_and_b32_e32 v19, 15, v18
	v_lshlrev_b32_e32 v21, 4, v20
	s_and_b32 s14, s1, 0x60
	v_lshlrev_b32_e32 v18, 2, v18
	v_or_b32_e32 v136, s46, v19
	v_lshl_or_b32 v19, v19, 6, v21
	s_lshl_b32 s1, s14, 7
	v_and_b32_e32 v18, 32, v18
	v_lshl_add_u64 v[10:11], v[10:11], 0, s[66:67]
	s_add_i32 m0, s31, 0x18000
	v_lshlrev_b32_e32 v22, 6, v136
	s_movk_i32 s10, 0x3c0
	v_bitop3_b32 v137, v19, s1, v18 bitop3:0xde
	global_load_lds_dwordx4 v[10:11], off
	v_lshl_add_u64 v[8:9], v[8:9], 0, s[66:67]
	s_add_i32 m0, s31, 0x1a000
	s_add_i32 s1, s31, 0x8000
	s_add_i32 s34, s31, 0xa000
	v_and_or_b32 v22, v22, s10, v21
	global_load_lds_dwordx4 v[8:9], off
	v_lshl_add_u64 v[4:5], v[4:5], 0, s[66:67]
	s_mov_b32 m0, s1
	s_add_u32 s10, s22, 0x80080
	global_load_lds_dwordx4 v[4:5], off
	v_lshl_add_u64 v[4:5], v[6:7], 0, s[66:67]
	s_mov_b32 m0, s34
	s_addc_u32 s11, s23, 0
	global_load_lds_dwordx4 v[4:5], off
	v_lshl_add_u64 v[4:5], s[10:11], 0, v[2:3]
	s_add_i32 m0, s31, 0x1c000
	v_lshlrev_b32_e32 v23, 2, v136
	global_load_lds_dwordx4 v[4:5], off
	v_lshl_add_u64 v[4:5], s[10:11], 0, v[0:1]
	s_add_i32 m0, s31, 0x1e000
	v_and_b32_e32 v23, 32, v23
	global_load_lds_dwordx4 v[4:5], off
	s_waitcnt vmcnt(8)
	s_barrier
	v_lshlrev_b32_e32 v4, 15, v12
	v_and_b32_e32 v4, 0xffff0000, v4
	v_lshl_add_u32 v4, v13, 12, v4
	v_and_b32_e32 v5, 1, v12
	v_lshl_or_b32 v4, v5, 6, v4
	v_lshl_add_u32 v132, v14, 1, v4
	v_lshlrev_b32_e32 v4, 15, v15
	v_and_b32_e32 v4, 0xffff0000, v4
	s_waitcnt vmcnt(6)
	v_lshl_add_u32 v4, v16, 12, v4
	v_and_b32_e32 v5, 1, v15
	v_bitop3_b32 v22, v22, s45, v23 bitop3:0xde
	v_lshl_or_b32 v4, v5, 6, v4
	v_lshl_or_b32 v138, v20, 2, s14
	v_mov_b32_e32 v133, v3
	v_lshl_add_u32 v134, v17, 1, v4
	v_mov_b32_e32 v135, v3
	s_mov_b32 s35, 0
	v_add_u32_e32 v139, 0, v22
	s_barrier
	s_branch .LBB0_488

.LBB0_1000:
	v_lshl_add_u64 v[12:13], s[24:25], 0, v[2:3]
	v_mov_b32_e32 v191, v3
	s_lshl_b32 s11, s10, 5
	v_lshl_add_u64 v[14:15], s[24:25], 0, v[190:191]
	v_mov_b32_e32 v1, v3
	s_and_b32 s11, s11, 0x60
	s_add_i32 m0, s21, 0x18000
	v_lshl_add_u64 v[12:13], v[12:13], 0, s[66:67]
	v_lshl_add_u64 v[16:17], s[22:23], 0, v[0:1]
	v_mov_b32_e32 v189, v3
	s_lshl_b32 s9, s8, 13
	s_lshl_b32 s14, s11, 7
	global_load_lds_dwordx4 v[12:13], off
	v_lshl_add_u64 v[12:13], v[14:15], 0, s[66:67]
	s_add_i32 m0, s21, 0x1a000
	s_add_i32 s41, s21, 0x8000
	s_add_i32 s42, s21, 0xa000
	v_lshl_add_u64 v[18:19], s[22:23], 0, v[188:189]
	global_load_lds_dwordx4 v[12:13], off
	v_lshl_add_u64 v[12:13], v[16:17], 0, s[66:67]
	s_mov_b32 m0, s41
	s_add_u32 s12, s24, 0x80080
	global_load_lds_dwordx4 v[12:13], off
	v_lshl_add_u64 v[12:13], v[18:19], 0, s[66:67]
	s_mov_b32 m0, s42
	s_addc_u32 s13, s25, 0
	global_load_lds_dwordx4 v[12:13], off
	s_add_i32 m0, s21, 0x1c000
	v_lshl_add_u64 v[12:13], s[12:13], 0, v[2:3]
	global_load_lds_dwordx4 v[12:13], off
	v_lshl_add_u64 v[12:13], s[12:13], 0, v[190:191]
	s_add_i32 m0, s21, 0x1e000
	v_bfe_u32 v11, v4, 4, 2
	global_load_lds_dwordx4 v[12:13], off
	s_waitcnt vmcnt(8)
	s_barrier
	v_and_b32_e32 v12, 15, v4
	v_lshlrev_b32_e32 v13, 4, v11
	v_lshlrev_b32_e32 v4, 2, v4
	v_lshl_or_b32 v218, s8, 6, v12
	v_lshl_or_b32 v12, v12, 6, v13
	v_and_b32_e32 v4, 32, v4
	v_bitop3_b32 v13, v12, s9, v4 bitop3:0xde
	v_bitop3_b32 v219, v12, s14, v4 bitop3:0xde
	v_lshlrev_b32_e32 v4, 15, v5
	v_and_b32_e32 v4, 0xffff0000, v4
	v_lshl_add_u32 v4, v6, 12, v4
	v_and_b32_e32 v5, 1, v5
	v_lshl_or_b32 v4, v5, 6, v4
	v_lshl_add_u32 v192, v7, 1, v4
	v_lshlrev_b32_e32 v4, 15, v8
	v_and_b32_e32 v4, 0xffff0000, v4
	s_waitcnt vmcnt(6)
	v_lshl_add_u32 v4, v9, 12, v4
	v_and_b32_e32 v5, 1, v8
	s_cmp_lt_u32 s10, 4
	v_lshl_or_b32 v4, v5, 6, v4
	s_cselect_b64 s[8:9], -1, 0
	s_mov_b32 s43, 0
	v_cmp_eq_u32_e64 s[36:37], 0, v11
	s_ashr_i32 s44, s0, 31
	v_lshl_or_b32 v220, v11, 3, s11
	v_mov_b32_e32 v193, v3
	v_lshl_add_u32 v194, v10, 1, v4
	v_mov_b32_e32 v195, v3
	v_add_u32_e32 v221, 0, v13
	s_barrier
	s_branch .LBB0_1003
